# grid barrier: XCD leader bumps the per-XCD generation flag before its own acquire invalidate (followers released earlier) + previous
# baseline (speedup 1.0000x reference)
.LBB0_118:
	s_or_b64 exec, exec, s[4:5]
	v_mov_b32_e32 v0, s1
	v_add_co_u32_e32 v0, vcc, 0x2000, v0
	v_mov_b32_e32 v1, s0
	s_nop 0
	v_addc_co_u32_e32 v1, vcc, 0, v1, vcc
	v_mov_b32_e32 v2, 1
	s_waitcnt vmcnt(0) lgkmcnt(0)
	flat_atomic_add v[0:1], v2 offset:1024
	buffer_inv sc1
	s_waitcnt vmcnt(0)

.LBB0_1770:
	s_or_b64 exec, exec, s[6:7]
	v_mov_b32_e32 v0, s1
	v_add_co_u32_e32 v0, vcc, 0x2000, v0
	v_mov_b32_e32 v1, s0
	s_nop 0
	v_addc_co_u32_e32 v1, vcc, 0, v1, vcc
	v_mov_b32_e32 v2, 1
	s_waitcnt vmcnt(0) lgkmcnt(0)
	flat_atomic_add v[0:1], v2 offset:1024
	buffer_inv sc1
	s_waitcnt vmcnt(0)

.LBB0_2964:
	s_or_b64 exec, exec, s[2:3]
	v_mov_b32_e32 v0, s1
	v_add_co_u32_e32 v0, vcc, 0x2000, v0
	v_mov_b32_e32 v1, s0
	s_nop 0
	v_addc_co_u32_e32 v1, vcc, 0, v1, vcc
	v_mov_b32_e32 v2, 1
	s_waitcnt vmcnt(0) lgkmcnt(0)
	flat_atomic_add v[0:1], v2 offset:1024
	buffer_inv sc1
	s_waitcnt vmcnt(0)
